# first seam uses the XCD barrier instead of cooperative-groups grid sync
# speedup vs baseline: 1.0149x; 1.0149x over previous
; __device__ __forceinline__ void xcd_barrier(const XcdBarrier& b) {
;     asm volatile("s_waitcnt vmcnt(0)" ::: "memory");
;     __syncthreads();
;     if (threadIdx.x == 0) {
;         unsigned* bar = b.bar;
;         __builtin_amdgcn_s_waitcnt(0);
;         unsigned nloc = b.st[0], nx = b.st[1];
;         if (nloc == 0u) { xcd_barrier_complete(bar, b.x, nloc, nx); b.st[0] = nloc; b.st[1] = nx; }
; __global__ void __launch_bounds__(512, 2) mega_fwd(Params Pin) {
;     ...
;         if (ph + 1 < ph_hi) { if (ph == ph_lo) grid.sync(); else xcd_barrier(xbar); }
.LBB0_522:
	s_add_i32 s4, s77, 1
	s_cmp_ge_i32 s4, s59
	s_mov_b64 s[0:1], -1
	s_cbranch_scc1 .LBB0_10
	s_waitcnt vmcnt(0)
	s_waitcnt lgkmcnt(0)
	s_barrier
	s_mov_b64 s[0:1], exec
	v_readlane_b32 s6, v254, 7
	v_readlane_b32 s7, v254, 8
	v_readlane_b32 s10, v254, 10
	v_readlane_b32 s18, v254, 12
	v_readlane_b32 s28, v254, 14
	v_readlane_b32 s38, v254, 16
	v_readlane_b32 s40, v254, 18
	v_readlane_b32 s42, v254, 20
	v_readlane_b32 s44, v254, 22
	v_readlane_b32 s46, v254, 24
	v_readlane_b32 s48, v254, 26
	v_readlane_b32 s50, v254, 28
	v_readlane_b32 s52, v254, 30
	v_readlane_b32 s54, v254, 32
	v_readlane_b32 s60, v254, 34
	v_readlane_b32 s64, v254, 36
	v_readlane_b32 s66, v254, 38
	v_readlane_b32 s68, v254, 40
	v_readlane_b32 s70, v254, 42
	v_readlane_b32 s72, v255, 14
	s_and_b64 s[6:7], s[0:1], s[6:7]
	v_readlane_b32 s8, v254, 9
	v_readlane_b32 s11, v254, 11
	v_readlane_b32 s19, v254, 13
	v_readlane_b32 s29, v254, 15
	v_readlane_b32 s39, v254, 17
	v_readlane_b32 s41, v254, 19
	v_readlane_b32 s43, v254, 21
	v_readlane_b32 s45, v254, 23
	v_readlane_b32 s47, v254, 25
	v_readlane_b32 s49, v254, 27
	v_readlane_b32 s51, v254, 29
	v_readlane_b32 s53, v254, 31
	v_readlane_b32 s55, v254, 33
	v_readlane_b32 s61, v254, 35
	v_readlane_b32 s65, v254, 37
	v_readlane_b32 s67, v254, 39
	v_readlane_b32 s69, v254, 41
	v_readlane_b32 s71, v254, 43
	v_readlane_b32 s73, v255, 15
	s_mov_b64 exec, s[6:7]
	s_cbranch_execz .LBB0_577
	v_readlane_b32 s5, v255, 22
	s_waitcnt vmcnt(0) expcnt(0) lgkmcnt(0)
	s_nop 0
	v_mov_b32_e32 v0, s5
	ds_read_b32 v3, v0
	v_readlane_b32 s5, v255, 23
	s_waitcnt lgkmcnt(0)
	v_cmp_ne_u32_e32 vcc, 0, v3
	v_mov_b32_e32 v0, s5
	ds_read_b32 v2, v0
	s_cbranch_vccnz .LBB0_541
	s_mov_b32 s5, 1
	s_branch .LBB0_528
